# hand-written SwiGLU epilogue of the gate/up GEMM: packed-f32 scale/bias and products, exp/rcp batched per row block, row-sum reads pipelined one block ahead, saddr stores
# speedup vs baseline: 1.0215x; 1.0075x over previous
; #define PG8_LAS __attribute__((address_space(3)))
; __device__ __forceinline__ unsigned cvt_pk_bf16(float lo, float hi) { unsigned r; asm volatile("v_cvt_pk_bf16_f32 %0, %1, %2" : "=v"(r) : "v"(lo), "v"(hi)); return r; }
;     __device__ __forceinline__ float silu(float x) const { return x * __builtin_amdgcn_rcpf(1.0f + __builtin_amdgcn_exp2f(-x * kLog2e)); }
;     __device__ __forceinline__ void operator()(const f32x4 (&acc)[2][2][4][2], const Unit& u, int wr, int wc, int fr, int fq) const {
;         const int row0 = u.pm * BM + wr * 64 + fr, col0 = u.pn * 128 + 32 * wc + 8 * fq;
;         P.issue(k + 1, wr == 0 && wc == 0, fr + 16 * fq);
;         PG8_LAS const float* slot = (PG8_LAS const float*)(P.pf + (k & 1) * 5120); ++k;
;         PG8_LAS const float* bp = slot + 1024 + 32 * wc + 8 * fq;
;         const f32x4 bg0 = *(PG8_LAS const f32x4*)(bp), bg1 = *(PG8_LAS const f32x4*)(bp + 4), bu0 = *(PG8_LAS const f32x4*)(bp + 128), bu1 = *(PG8_LAS const f32x4*)(bp + 132);
;         float rr[2][4];
; #pragma unroll
;         for (int ai = 0; ai < 2; ++ai)
; #pragma unroll
;             for (int m = 0; m < 4; ++m) { const f32x4 t = *(PG8_LAS const f32x4*)(slot + 4 * (wr * 64 + fr + ai * HALF + m * 16)); rr[ai][m] = (t[0] + t[1]) + (t[2] + t[3]); }
; #pragma unroll
;         for (int ai = 0; ai < 2; ++ai)
; #pragma unroll
;             for (int m = 0; m < 4; ++m) {
;                 const int row = row0 + ai * HALF + m * 16;
;                 const float r = __builtin_amdgcn_rsqf(rr[ai][m] * (1.0f / 1024.0f) + 1e-6f);
;                 const f32x4 g0 = acc[ai][0][m][0] * r + bg0, g1 = acc[ai][0][m][1] * r + bg1, u0 = acc[ai][1][m][0] * r + bu0, u1 = acc[ai][1][m][1] * r + bu1;
;                 u32x4 w; w.x = cvt_pk_bf16(silu(g0[0]) * u0[0], silu(g0[1]) * u0[1]); w.y = cvt_pk_bf16(silu(g0[2]) * u0[2], silu(g0[3]) * u0[3]);
;                 w.z = cvt_pk_bf16(silu(g1[0]) * u1[0], silu(g1[1]) * u1[1]); w.w = cvt_pk_bf16(silu(g1[2]) * u1[2], silu(g1[3]) * u1[3]);
;                 *(u32x4*)(Aout + (size_t)row * 2816 + col0) = w;
.LBB0_67:
	s_bitcmp1_b32 s27, 0
	s_cselect_b32 s2, 0x1400, 0
	s_add_i32 s2, s2, 0x20000
	s_lshl_b32 s3, s69, 2
	s_add_i32 s3, s2, s3
	v_lshl_add_u32 v158, v161, 2, s3
	v_add_u32_e32 v159, s2, v163
	ds_read_b128 v[176:179], v159
	ds_read_b128 v[78:81], v158 offset:4096
	ds_read_b128 v[70:73], v158 offset:4112
	ds_read_b128 v[66:69], v158 offset:4608
	ds_read_b128 v[62:65], v158 offset:4624
	v_lshl_or_b32 v167, s60, 7, v164
	v_lshl_add_u32 v169, s61, 8, v160
	v_lshlrev_b32_e32 v167, 1, v167
	v_mad_u32_u24 v167, v169, s54, v167
	s_mov_b32 s2, 0xbfb8aa3b
	s_mov_b32 s3, 1.0
	s_waitcnt lgkmcnt(0)
	v_add_f32_e32 v168, v176, v177
	v_add_f32_e32 v169, v178, v179
	v_add_f32_e32 v168, v168, v169
	v_fmamk_f32 v168, v168, 0x3a800000, v225
	v_rsq_f32_e32 v168, v168
	ds_read_b128 v[176:179], v159 offset:256
	v_pk_fma_f32 v[142:143], v[142:143], v[168:169], v[78:79] op_sel_hi:[1,0,1]
	v_pk_fma_f32 v[144:145], v[144:145], v[168:169], v[80:81] op_sel_hi:[1,0,1]
	v_pk_fma_f32 v[138:139], v[138:139], v[168:169], v[70:71] op_sel_hi:[1,0,1]
	v_pk_fma_f32 v[140:141], v[140:141], v[168:169], v[72:73] op_sel_hi:[1,0,1]
	v_pk_fma_f32 v[134:135], v[134:135], v[168:169], v[66:67] op_sel_hi:[1,0,1]
	v_pk_fma_f32 v[136:137], v[136:137], v[168:169], v[68:69] op_sel_hi:[1,0,1]
	v_pk_fma_f32 v[130:131], v[130:131], v[168:169], v[62:63] op_sel_hi:[1,0,1]
	v_pk_fma_f32 v[132:133], v[132:133], v[168:169], v[64:65] op_sel_hi:[1,0,1]
	v_pk_mul_f32 v[170:171], v[142:143], s[2:3] op_sel_hi:[1,0]
	v_pk_mul_f32 v[172:173], v[144:145], s[2:3] op_sel_hi:[1,0]
	v_pk_mul_f32 v[174:175], v[138:139], s[2:3] op_sel_hi:[1,0]
	v_pk_mul_f32 v[180:181], v[140:141], s[2:3] op_sel_hi:[1,0]
	v_exp_f32_e32 v170, v170
	v_exp_f32_e32 v171, v171
	v_exp_f32_e32 v172, v172
	v_exp_f32_e32 v173, v173
	v_exp_f32_e32 v174, v174
	v_exp_f32_e32 v175, v175
	v_exp_f32_e32 v180, v180
	v_exp_f32_e32 v181, v181
	v_pk_add_f32 v[170:171], v[170:171], s[2:3] op_sel:[0,1] op_sel_hi:[1,1]
	v_pk_add_f32 v[172:173], v[172:173], s[2:3] op_sel:[0,1] op_sel_hi:[1,1]
	v_pk_add_f32 v[174:175], v[174:175], s[2:3] op_sel:[0,1] op_sel_hi:[1,1]
	v_pk_add_f32 v[180:181], v[180:181], s[2:3] op_sel:[0,1] op_sel_hi:[1,1]
	v_rcp_f32_e32 v170, v170
	v_rcp_f32_e32 v171, v171
	v_rcp_f32_e32 v172, v172
	v_rcp_f32_e32 v173, v173
	v_rcp_f32_e32 v174, v174
	v_rcp_f32_e32 v175, v175
	v_rcp_f32_e32 v180, v180
	v_rcp_f32_e32 v181, v181
	v_pk_mul_f32 v[142:143], v[142:143], v[170:171]
	v_pk_mul_f32 v[144:145], v[144:145], v[172:173]
	v_pk_mul_f32 v[138:139], v[138:139], v[174:175]
	v_pk_mul_f32 v[140:141], v[140:141], v[180:181]
	v_pk_mul_f32 v[142:143], v[134:135], v[142:143]
	v_pk_mul_f32 v[144:145], v[136:137], v[144:145]
	v_pk_mul_f32 v[138:139], v[130:131], v[138:139]
	v_pk_mul_f32 v[140:141], v[132:133], v[140:141]
	v_cvt_pk_bf16_f32 v130, v142, v143
	v_cvt_pk_bf16_f32 v131, v144, v145
	v_cvt_pk_bf16_f32 v132, v138, v139
	v_cvt_pk_bf16_f32 v133, v140, v141
	global_store_dwordx4 v167, v[130:133], s[84:85]
	s_waitcnt lgkmcnt(0)
	v_add_f32_e32 v168, v176, v177
	v_add_f32_e32 v169, v178, v179
	v_add_f32_e32 v168, v168, v169
	v_fmamk_f32 v168, v168, 0x3a800000, v225
	v_rsq_f32_e32 v168, v168
	ds_read_b128 v[176:179], v159 offset:512
	v_pk_fma_f32 v[126:127], v[126:127], v[168:169], v[78:79] op_sel_hi:[1,0,1]
	v_pk_fma_f32 v[128:129], v[128:129], v[168:169], v[80:81] op_sel_hi:[1,0,1]
	v_pk_fma_f32 v[122:123], v[122:123], v[168:169], v[70:71] op_sel_hi:[1,0,1]
	v_pk_fma_f32 v[124:125], v[124:125], v[168:169], v[72:73] op_sel_hi:[1,0,1]
	v_pk_fma_f32 v[118:119], v[118:119], v[168:169], v[66:67] op_sel_hi:[1,0,1]
	v_pk_fma_f32 v[120:121], v[120:121], v[168:169], v[68:69] op_sel_hi:[1,0,1]
	v_pk_fma_f32 v[114:115], v[114:115], v[168:169], v[62:63] op_sel_hi:[1,0,1]
	v_pk_fma_f32 v[116:117], v[116:117], v[168:169], v[64:65] op_sel_hi:[1,0,1]
	v_pk_mul_f32 v[170:171], v[126:127], s[2:3] op_sel_hi:[1,0]
	v_pk_mul_f32 v[172:173], v[128:129], s[2:3] op_sel_hi:[1,0]
	v_pk_mul_f32 v[174:175], v[122:123], s[2:3] op_sel_hi:[1,0]
	v_pk_mul_f32 v[180:181], v[124:125], s[2:3] op_sel_hi:[1,0]
	v_exp_f32_e32 v170, v170
	v_exp_f32_e32 v171, v171
	v_exp_f32_e32 v172, v172
	v_exp_f32_e32 v173, v173
	v_exp_f32_e32 v174, v174
	v_exp_f32_e32 v175, v175
	v_exp_f32_e32 v180, v180
	v_exp_f32_e32 v181, v181
	v_pk_add_f32 v[170:171], v[170:171], s[2:3] op_sel:[0,1] op_sel_hi:[1,1]
	v_pk_add_f32 v[172:173], v[172:173], s[2:3] op_sel:[0,1] op_sel_hi:[1,1]
	v_pk_add_f32 v[174:175], v[174:175], s[2:3] op_sel:[0,1] op_sel_hi:[1,1]
	v_pk_add_f32 v[180:181], v[180:181], s[2:3] op_sel:[0,1] op_sel_hi:[1,1]
	v_rcp_f32_e32 v170, v170
	v_rcp_f32_e32 v171, v171
	v_rcp_f32_e32 v172, v172
	v_rcp_f32_e32 v173, v173
	v_rcp_f32_e32 v174, v174
	v_rcp_f32_e32 v175, v175
	v_rcp_f32_e32 v180, v180
	v_rcp_f32_e32 v181, v181
	v_pk_mul_f32 v[126:127], v[126:127], v[170:171]
	v_pk_mul_f32 v[128:129], v[128:129], v[172:173]
	v_pk_mul_f32 v[122:123], v[122:123], v[174:175]
	v_pk_mul_f32 v[124:125], v[124:125], v[180:181]
	v_pk_mul_f32 v[126:127], v[118:119], v[126:127]
	v_pk_mul_f32 v[128:129], v[120:121], v[128:129]
	v_pk_mul_f32 v[122:123], v[114:115], v[122:123]
	v_pk_mul_f32 v[124:125], v[116:117], v[124:125]
	v_add_u32_e32 v158, 0x16000, v167
	v_cvt_pk_bf16_f32 v114, v126, v127
	v_cvt_pk_bf16_f32 v115, v128, v129
	v_cvt_pk_bf16_f32 v116, v122, v123
	v_cvt_pk_bf16_f32 v117, v124, v125
	global_store_dwordx4 v158, v[114:117], s[84:85]
	s_waitcnt lgkmcnt(0)
; __device__ __forceinline__ unsigned cvt_pk_bf16(float lo, float hi) { unsigned r; asm volatile("v_cvt_pk_bf16_f32 %0, %1, %2" : "=v"(r) : "v"(lo), "v"(hi)); return r; }
;     __device__ __forceinline__ float silu(float x) const { return x * __builtin_amdgcn_rcpf(1.0f + __builtin_amdgcn_exp2f(-x * kLog2e)); }
;     __device__ __forceinline__ void operator()(const f32x4 (&acc)[2][2][4][2], const Unit& u, int wr, int wc, int fr, int fq) const {
;     ...
;         for (int ai = 0; ai < 2; ++ai)
; #pragma unroll
;             for (int m = 0; m < 4; ++m) {
;                 const int row = row0 + ai * HALF + m * 16;
;                 const float r = __builtin_amdgcn_rsqf(rr[ai][m] * (1.0f / 1024.0f) + 1e-6f);
;                 const f32x4 g0 = acc[ai][0][m][0] * r + bg0, g1 = acc[ai][0][m][1] * r + bg1, u0 = acc[ai][1][m][0] * r + bu0, u1 = acc[ai][1][m][1] * r + bu1;
;                 u32x4 w; w.x = cvt_pk_bf16(silu(g0[0]) * u0[0], silu(g0[1]) * u0[1]); w.y = cvt_pk_bf16(silu(g0[2]) * u0[2], silu(g0[3]) * u0[3]);
;                 w.z = cvt_pk_bf16(silu(g1[0]) * u1[0], silu(g1[1]) * u1[1]); w.w = cvt_pk_bf16(silu(g1[2]) * u1[2], silu(g1[3]) * u1[3]);
;                 *(u32x4*)(Aout + (size_t)row * 2816 + col0) = w;
	v_add_f32_e32 v168, v176, v177
	v_add_f32_e32 v169, v178, v179
	v_add_f32_e32 v168, v168, v169
	v_fmamk_f32 v168, v168, 0x3a800000, v225
	v_rsq_f32_e32 v168, v168
	ds_read_b128 v[176:179], v159 offset:768
	v_pk_fma_f32 v[110:111], v[110:111], v[168:169], v[78:79] op_sel_hi:[1,0,1]
	v_pk_fma_f32 v[112:113], v[112:113], v[168:169], v[80:81] op_sel_hi:[1,0,1]
	v_pk_fma_f32 v[106:107], v[106:107], v[168:169], v[70:71] op_sel_hi:[1,0,1]
	v_pk_fma_f32 v[108:109], v[108:109], v[168:169], v[72:73] op_sel_hi:[1,0,1]
	v_pk_fma_f32 v[102:103], v[102:103], v[168:169], v[66:67] op_sel_hi:[1,0,1]
	v_pk_fma_f32 v[104:105], v[104:105], v[168:169], v[68:69] op_sel_hi:[1,0,1]
	v_pk_fma_f32 v[98:99], v[98:99], v[168:169], v[62:63] op_sel_hi:[1,0,1]
	v_pk_fma_f32 v[100:101], v[100:101], v[168:169], v[64:65] op_sel_hi:[1,0,1]
	v_pk_mul_f32 v[170:171], v[110:111], s[2:3] op_sel_hi:[1,0]
	v_pk_mul_f32 v[172:173], v[112:113], s[2:3] op_sel_hi:[1,0]
	v_pk_mul_f32 v[174:175], v[106:107], s[2:3] op_sel_hi:[1,0]
	v_pk_mul_f32 v[180:181], v[108:109], s[2:3] op_sel_hi:[1,0]
	v_exp_f32_e32 v170, v170
	v_exp_f32_e32 v171, v171
	v_exp_f32_e32 v172, v172
	v_exp_f32_e32 v173, v173
	v_exp_f32_e32 v174, v174
	v_exp_f32_e32 v175, v175
	v_exp_f32_e32 v180, v180
	v_exp_f32_e32 v181, v181
	v_pk_add_f32 v[170:171], v[170:171], s[2:3] op_sel:[0,1] op_sel_hi:[1,1]
	v_pk_add_f32 v[172:173], v[172:173], s[2:3] op_sel:[0,1] op_sel_hi:[1,1]
	v_pk_add_f32 v[174:175], v[174:175], s[2:3] op_sel:[0,1] op_sel_hi:[1,1]
	v_pk_add_f32 v[180:181], v[180:181], s[2:3] op_sel:[0,1] op_sel_hi:[1,1]
	v_rcp_f32_e32 v170, v170
	v_rcp_f32_e32 v171, v171
	v_rcp_f32_e32 v172, v172
	v_rcp_f32_e32 v173, v173
	v_rcp_f32_e32 v174, v174
	v_rcp_f32_e32 v175, v175
	v_rcp_f32_e32 v180, v180
	v_rcp_f32_e32 v181, v181
	v_pk_mul_f32 v[110:111], v[110:111], v[170:171]
	v_pk_mul_f32 v[112:113], v[112:113], v[172:173]
	v_pk_mul_f32 v[106:107], v[106:107], v[174:175]
	v_pk_mul_f32 v[108:109], v[108:109], v[180:181]
	v_pk_mul_f32 v[110:111], v[102:103], v[110:111]
	v_pk_mul_f32 v[112:113], v[104:105], v[112:113]
	v_pk_mul_f32 v[106:107], v[98:99], v[106:107]
	v_pk_mul_f32 v[108:109], v[100:101], v[108:109]
	v_add_u32_e32 v158, 0x2c000, v167
	v_cvt_pk_bf16_f32 v98, v110, v111
	v_cvt_pk_bf16_f32 v99, v112, v113
	v_cvt_pk_bf16_f32 v100, v106, v107
	v_cvt_pk_bf16_f32 v101, v108, v109
	global_store_dwordx4 v158, v[98:101], s[84:85]
	s_waitcnt lgkmcnt(0)
	v_add_f32_e32 v168, v176, v177
	v_add_f32_e32 v169, v178, v179
	v_add_f32_e32 v168, v168, v169
	v_fmamk_f32 v168, v168, 0x3a800000, v225
	v_rsq_f32_e32 v168, v168
	ds_read_b128 v[176:179], v159 offset:2048
	v_pk_fma_f32 v[94:95], v[94:95], v[168:169], v[78:79] op_sel_hi:[1,0,1]
	v_pk_fma_f32 v[96:97], v[96:97], v[168:169], v[80:81] op_sel_hi:[1,0,1]
	v_pk_fma_f32 v[90:91], v[90:91], v[168:169], v[70:71] op_sel_hi:[1,0,1]
	v_pk_fma_f32 v[92:93], v[92:93], v[168:169], v[72:73] op_sel_hi:[1,0,1]
	v_pk_fma_f32 v[86:87], v[86:87], v[168:169], v[66:67] op_sel_hi:[1,0,1]
	v_pk_fma_f32 v[88:89], v[88:89], v[168:169], v[68:69] op_sel_hi:[1,0,1]
	v_pk_fma_f32 v[82:83], v[82:83], v[168:169], v[62:63] op_sel_hi:[1,0,1]
	v_pk_fma_f32 v[84:85], v[84:85], v[168:169], v[64:65] op_sel_hi:[1,0,1]
	v_pk_mul_f32 v[170:171], v[94:95], s[2:3] op_sel_hi:[1,0]
	v_pk_mul_f32 v[172:173], v[96:97], s[2:3] op_sel_hi:[1,0]
	v_pk_mul_f32 v[174:175], v[90:91], s[2:3] op_sel_hi:[1,0]
	v_pk_mul_f32 v[180:181], v[92:93], s[2:3] op_sel_hi:[1,0]
	v_exp_f32_e32 v170, v170
	v_exp_f32_e32 v171, v171
	v_exp_f32_e32 v172, v172
	v_exp_f32_e32 v173, v173
	v_exp_f32_e32 v174, v174
	v_exp_f32_e32 v175, v175
	v_exp_f32_e32 v180, v180
	v_exp_f32_e32 v181, v181
	v_pk_add_f32 v[170:171], v[170:171], s[2:3] op_sel:[0,1] op_sel_hi:[1,1]
	v_pk_add_f32 v[172:173], v[172:173], s[2:3] op_sel:[0,1] op_sel_hi:[1,1]
	v_pk_add_f32 v[174:175], v[174:175], s[2:3] op_sel:[0,1] op_sel_hi:[1,1]
	v_pk_add_f32 v[180:181], v[180:181], s[2:3] op_sel:[0,1] op_sel_hi:[1,1]
	v_rcp_f32_e32 v170, v170
	v_rcp_f32_e32 v171, v171
	v_rcp_f32_e32 v172, v172
	v_rcp_f32_e32 v173, v173
	v_rcp_f32_e32 v174, v174
	v_rcp_f32_e32 v175, v175
	v_rcp_f32_e32 v180, v180
	v_rcp_f32_e32 v181, v181
	v_pk_mul_f32 v[94:95], v[94:95], v[170:171]
	v_pk_mul_f32 v[96:97], v[96:97], v[172:173]
	v_pk_mul_f32 v[90:91], v[90:91], v[174:175]
	v_pk_mul_f32 v[92:93], v[92:93], v[180:181]
	v_pk_mul_f32 v[94:95], v[86:87], v[94:95]
	v_pk_mul_f32 v[96:97], v[88:89], v[96:97]
	v_pk_mul_f32 v[90:91], v[82:83], v[90:91]
	v_pk_mul_f32 v[92:93], v[84:85], v[92:93]
	v_add_u32_e32 v158, 0x42000, v167
	v_cvt_pk_bf16_f32 v82, v94, v95
	v_cvt_pk_bf16_f32 v83, v96, v97
	v_cvt_pk_bf16_f32 v84, v90, v91
	v_cvt_pk_bf16_f32 v85, v92, v93
	global_store_dwordx4 v158, v[82:85], s[84:85]
	s_waitcnt lgkmcnt(0)
; __device__ __forceinline__ unsigned cvt_pk_bf16(float lo, float hi) { unsigned r; asm volatile("v_cvt_pk_bf16_f32 %0, %1, %2" : "=v"(r) : "v"(lo), "v"(hi)); return r; }
;     __device__ __forceinline__ float silu(float x) const { return x * __builtin_amdgcn_rcpf(1.0f + __builtin_amdgcn_exp2f(-x * kLog2e)); }
;     __device__ __forceinline__ void operator()(const f32x4 (&acc)[2][2][4][2], const Unit& u, int wr, int wc, int fr, int fq) const {
;     ...
;         for (int ai = 0; ai < 2; ++ai)
; #pragma unroll
;             for (int m = 0; m < 4; ++m) {
;                 const int row = row0 + ai * HALF + m * 16;
;                 const float r = __builtin_amdgcn_rsqf(rr[ai][m] * (1.0f / 1024.0f) + 1e-6f);
;                 const f32x4 g0 = acc[ai][0][m][0] * r + bg0, g1 = acc[ai][0][m][1] * r + bg1, u0 = acc[ai][1][m][0] * r + bu0, u1 = acc[ai][1][m][1] * r + bu1;
;                 u32x4 w; w.x = cvt_pk_bf16(silu(g0[0]) * u0[0], silu(g0[1]) * u0[1]); w.y = cvt_pk_bf16(silu(g0[2]) * u0[2], silu(g0[3]) * u0[3]);
;                 w.z = cvt_pk_bf16(silu(g1[0]) * u1[0], silu(g1[1]) * u1[1]); w.w = cvt_pk_bf16(silu(g1[2]) * u1[2], silu(g1[3]) * u1[3]);
;                 *(u32x4*)(Aout + (size_t)row * 2816 + col0) = w;
	v_add_f32_e32 v168, v176, v177
	v_add_f32_e32 v169, v178, v179
	v_add_f32_e32 v168, v168, v169
	v_fmamk_f32 v168, v168, 0x3a800000, v225
	v_rsq_f32_e32 v168, v168
	ds_read_b128 v[176:179], v159 offset:2304
	v_pk_fma_f32 v[74:75], v[74:75], v[168:169], v[78:79] op_sel_hi:[1,0,1]
	v_pk_fma_f32 v[76:77], v[76:77], v[168:169], v[80:81] op_sel_hi:[1,0,1]
	v_pk_fma_f32 v[58:59], v[58:59], v[168:169], v[70:71] op_sel_hi:[1,0,1]
	v_pk_fma_f32 v[60:61], v[60:61], v[168:169], v[72:73] op_sel_hi:[1,0,1]
	v_pk_fma_f32 v[54:55], v[54:55], v[168:169], v[66:67] op_sel_hi:[1,0,1]
	v_pk_fma_f32 v[56:57], v[56:57], v[168:169], v[68:69] op_sel_hi:[1,0,1]
	v_pk_fma_f32 v[50:51], v[50:51], v[168:169], v[62:63] op_sel_hi:[1,0,1]
	v_pk_fma_f32 v[52:53], v[52:53], v[168:169], v[64:65] op_sel_hi:[1,0,1]
	v_pk_mul_f32 v[170:171], v[74:75], s[2:3] op_sel_hi:[1,0]
	v_pk_mul_f32 v[172:173], v[76:77], s[2:3] op_sel_hi:[1,0]
	v_pk_mul_f32 v[174:175], v[58:59], s[2:3] op_sel_hi:[1,0]
	v_pk_mul_f32 v[180:181], v[60:61], s[2:3] op_sel_hi:[1,0]
	v_exp_f32_e32 v170, v170
	v_exp_f32_e32 v171, v171
	v_exp_f32_e32 v172, v172
	v_exp_f32_e32 v173, v173
	v_exp_f32_e32 v174, v174
	v_exp_f32_e32 v175, v175
	v_exp_f32_e32 v180, v180
	v_exp_f32_e32 v181, v181
	v_pk_add_f32 v[170:171], v[170:171], s[2:3] op_sel:[0,1] op_sel_hi:[1,1]
	v_pk_add_f32 v[172:173], v[172:173], s[2:3] op_sel:[0,1] op_sel_hi:[1,1]
	v_pk_add_f32 v[174:175], v[174:175], s[2:3] op_sel:[0,1] op_sel_hi:[1,1]
	v_pk_add_f32 v[180:181], v[180:181], s[2:3] op_sel:[0,1] op_sel_hi:[1,1]
	v_rcp_f32_e32 v170, v170
	v_rcp_f32_e32 v171, v171
	v_rcp_f32_e32 v172, v172
	v_rcp_f32_e32 v173, v173
	v_rcp_f32_e32 v174, v174
	v_rcp_f32_e32 v175, v175
	v_rcp_f32_e32 v180, v180
	v_rcp_f32_e32 v181, v181
	v_pk_mul_f32 v[74:75], v[74:75], v[170:171]
	v_pk_mul_f32 v[76:77], v[76:77], v[172:173]
	v_pk_mul_f32 v[58:59], v[58:59], v[174:175]
	v_pk_mul_f32 v[60:61], v[60:61], v[180:181]
	v_pk_mul_f32 v[74:75], v[54:55], v[74:75]
	v_pk_mul_f32 v[76:77], v[56:57], v[76:77]
	v_pk_mul_f32 v[58:59], v[50:51], v[58:59]
	v_pk_mul_f32 v[60:61], v[52:53], v[60:61]
	v_add_u32_e32 v158, 0xb0000, v167
	v_cvt_pk_bf16_f32 v50, v74, v75
	v_cvt_pk_bf16_f32 v51, v76, v77
	v_cvt_pk_bf16_f32 v52, v58, v59
	v_cvt_pk_bf16_f32 v53, v60, v61
	global_store_dwordx4 v158, v[50:53], s[84:85]
	s_waitcnt lgkmcnt(0)
	v_add_f32_e32 v168, v176, v177
	v_add_f32_e32 v169, v178, v179
	v_add_f32_e32 v168, v168, v169
	v_fmamk_f32 v168, v168, 0x3a800000, v225
	v_rsq_f32_e32 v168, v168
	ds_read_b128 v[176:179], v159 offset:2560
	v_pk_fma_f32 v[46:47], v[46:47], v[168:169], v[78:79] op_sel_hi:[1,0,1]
	v_pk_fma_f32 v[48:49], v[48:49], v[168:169], v[80:81] op_sel_hi:[1,0,1]
	v_pk_fma_f32 v[42:43], v[42:43], v[168:169], v[70:71] op_sel_hi:[1,0,1]
	v_pk_fma_f32 v[44:45], v[44:45], v[168:169], v[72:73] op_sel_hi:[1,0,1]
	v_pk_fma_f32 v[38:39], v[38:39], v[168:169], v[66:67] op_sel_hi:[1,0,1]
	v_pk_fma_f32 v[40:41], v[40:41], v[168:169], v[68:69] op_sel_hi:[1,0,1]
	v_pk_fma_f32 v[34:35], v[34:35], v[168:169], v[62:63] op_sel_hi:[1,0,1]
	v_pk_fma_f32 v[36:37], v[36:37], v[168:169], v[64:65] op_sel_hi:[1,0,1]
	v_pk_mul_f32 v[170:171], v[46:47], s[2:3] op_sel_hi:[1,0]
	v_pk_mul_f32 v[172:173], v[48:49], s[2:3] op_sel_hi:[1,0]
	v_pk_mul_f32 v[174:175], v[42:43], s[2:3] op_sel_hi:[1,0]
	v_pk_mul_f32 v[180:181], v[44:45], s[2:3] op_sel_hi:[1,0]
	v_exp_f32_e32 v170, v170
	v_exp_f32_e32 v171, v171
	v_exp_f32_e32 v172, v172
	v_exp_f32_e32 v173, v173
	v_exp_f32_e32 v174, v174
	v_exp_f32_e32 v175, v175
	v_exp_f32_e32 v180, v180
	v_exp_f32_e32 v181, v181
	v_pk_add_f32 v[170:171], v[170:171], s[2:3] op_sel:[0,1] op_sel_hi:[1,1]
	v_pk_add_f32 v[172:173], v[172:173], s[2:3] op_sel:[0,1] op_sel_hi:[1,1]
	v_pk_add_f32 v[174:175], v[174:175], s[2:3] op_sel:[0,1] op_sel_hi:[1,1]
	v_pk_add_f32 v[180:181], v[180:181], s[2:3] op_sel:[0,1] op_sel_hi:[1,1]
	v_rcp_f32_e32 v170, v170
	v_rcp_f32_e32 v171, v171
	v_rcp_f32_e32 v172, v172
	v_rcp_f32_e32 v173, v173
	v_rcp_f32_e32 v174, v174
	v_rcp_f32_e32 v175, v175
	v_rcp_f32_e32 v180, v180
	v_rcp_f32_e32 v181, v181
	v_pk_mul_f32 v[46:47], v[46:47], v[170:171]
	v_pk_mul_f32 v[48:49], v[48:49], v[172:173]
	v_pk_mul_f32 v[42:43], v[42:43], v[174:175]
	v_pk_mul_f32 v[44:45], v[44:45], v[180:181]
	v_pk_mul_f32 v[46:47], v[38:39], v[46:47]
	v_pk_mul_f32 v[48:49], v[40:41], v[48:49]
	v_pk_mul_f32 v[42:43], v[34:35], v[42:43]
	v_pk_mul_f32 v[44:45], v[36:37], v[44:45]
	v_add_u32_e32 v158, 0xc6000, v167
	v_cvt_pk_bf16_f32 v34, v46, v47
	v_cvt_pk_bf16_f32 v35, v48, v49
	v_cvt_pk_bf16_f32 v36, v42, v43
	v_cvt_pk_bf16_f32 v37, v44, v45
	global_store_dwordx4 v158, v[34:37], s[84:85]
	s_waitcnt lgkmcnt(0)
; __device__ __forceinline__ unsigned cvt_pk_bf16(float lo, float hi) { unsigned r; asm volatile("v_cvt_pk_bf16_f32 %0, %1, %2" : "=v"(r) : "v"(lo), "v"(hi)); return r; }
;     __device__ __forceinline__ float silu(float x) const { return x * __builtin_amdgcn_rcpf(1.0f + __builtin_amdgcn_exp2f(-x * kLog2e)); }
; #define PG8_BAR __builtin_amdgcn_s_barrier()
;     __device__ __forceinline__ void operator()(const f32x4 (&acc)[2][2][4][2], const Unit& u, int wr, int wc, int fr, int fq) const {
;     ...
;         for (int ai = 0; ai < 2; ++ai)
; #pragma unroll
;             for (int m = 0; m < 4; ++m) {
;                 const int row = row0 + ai * HALF + m * 16;
;                 const float r = __builtin_amdgcn_rsqf(rr[ai][m] * (1.0f / 1024.0f) + 1e-6f);
;                 const f32x4 g0 = acc[ai][0][m][0] * r + bg0, g1 = acc[ai][0][m][1] * r + bg1, u0 = acc[ai][1][m][0] * r + bu0, u1 = acc[ai][1][m][1] * r + bu1;
;                 u32x4 w; w.x = cvt_pk_bf16(silu(g0[0]) * u0[0], silu(g0[1]) * u0[1]); w.y = cvt_pk_bf16(silu(g0[2]) * u0[2], silu(g0[3]) * u0[3]);
;                 w.z = cvt_pk_bf16(silu(g1[0]) * u1[0], silu(g1[1]) * u1[1]); w.w = cvt_pk_bf16(silu(g1[2]) * u1[2], silu(g1[3]) * u1[3]);
;                 *(u32x4*)(Aout + (size_t)row * 2816 + col0) = w;
; template <class Epi, class Sched, bool ALIGN_EPI = false, bool SP2 = false>
; __device__ __forceinline__ void gemm_phase(PG8_LAS unsigned char* lds, const Gemm g, const Sched& S, const Epi& E, const int tid) {
;     ...
;         if (!has_next) break;
; #pragma unroll
;         for (int a = 0; a < 2; ++a)
; #pragma unroll
;             for (int b = 0; b < 2; ++b)
; #pragma unroll
;                 for (int m = 0; m < 4; ++m)
; #pragma unroll
;                     for (int n = 0; n < 2; ++n) acc[a][b][m][n] = (f32x4){0.f, 0.f, 0.f, 0.f};
;         cur = nxt; cA = nA; cB = nB; ++ui;
;         if constexpr (ALIGN_EPI) { if (wr == 1) PG8_BAR; }
	v_add_f32_e32 v168, v176, v177
	v_add_f32_e32 v169, v178, v179
	v_add_f32_e32 v168, v168, v169
	v_fmamk_f32 v168, v168, 0x3a800000, v225
	v_rsq_f32_e32 v168, v168
	ds_read_b128 v[176:179], v159 offset:2816
	v_pk_fma_f32 v[30:31], v[30:31], v[168:169], v[78:79] op_sel_hi:[1,0,1]
	v_pk_fma_f32 v[32:33], v[32:33], v[168:169], v[80:81] op_sel_hi:[1,0,1]
	v_pk_fma_f32 v[26:27], v[26:27], v[168:169], v[70:71] op_sel_hi:[1,0,1]
	v_pk_fma_f32 v[28:29], v[28:29], v[168:169], v[72:73] op_sel_hi:[1,0,1]
	v_pk_fma_f32 v[22:23], v[22:23], v[168:169], v[66:67] op_sel_hi:[1,0,1]
	v_pk_fma_f32 v[24:25], v[24:25], v[168:169], v[68:69] op_sel_hi:[1,0,1]
	v_pk_fma_f32 v[18:19], v[18:19], v[168:169], v[62:63] op_sel_hi:[1,0,1]
	v_pk_fma_f32 v[20:21], v[20:21], v[168:169], v[64:65] op_sel_hi:[1,0,1]
	v_pk_mul_f32 v[170:171], v[30:31], s[2:3] op_sel_hi:[1,0]
	v_pk_mul_f32 v[172:173], v[32:33], s[2:3] op_sel_hi:[1,0]
	v_pk_mul_f32 v[174:175], v[26:27], s[2:3] op_sel_hi:[1,0]
	v_pk_mul_f32 v[180:181], v[28:29], s[2:3] op_sel_hi:[1,0]
	v_exp_f32_e32 v170, v170
	v_exp_f32_e32 v171, v171
	v_exp_f32_e32 v172, v172
	v_exp_f32_e32 v173, v173
	v_exp_f32_e32 v174, v174
	v_exp_f32_e32 v175, v175
	v_exp_f32_e32 v180, v180
	v_exp_f32_e32 v181, v181
	v_pk_add_f32 v[170:171], v[170:171], s[2:3] op_sel:[0,1] op_sel_hi:[1,1]
	v_pk_add_f32 v[172:173], v[172:173], s[2:3] op_sel:[0,1] op_sel_hi:[1,1]
	v_pk_add_f32 v[174:175], v[174:175], s[2:3] op_sel:[0,1] op_sel_hi:[1,1]
	v_pk_add_f32 v[180:181], v[180:181], s[2:3] op_sel:[0,1] op_sel_hi:[1,1]
	v_rcp_f32_e32 v170, v170
	v_rcp_f32_e32 v171, v171
	v_rcp_f32_e32 v172, v172
	v_rcp_f32_e32 v173, v173
	v_rcp_f32_e32 v174, v174
	v_rcp_f32_e32 v175, v175
	v_rcp_f32_e32 v180, v180
	v_rcp_f32_e32 v181, v181
	v_pk_mul_f32 v[30:31], v[30:31], v[170:171]
	v_pk_mul_f32 v[32:33], v[32:33], v[172:173]
	v_pk_mul_f32 v[26:27], v[26:27], v[174:175]
	v_pk_mul_f32 v[28:29], v[28:29], v[180:181]
	v_pk_mul_f32 v[30:31], v[22:23], v[30:31]
	v_pk_mul_f32 v[32:33], v[24:25], v[32:33]
	v_pk_mul_f32 v[26:27], v[18:19], v[26:27]
	v_pk_mul_f32 v[28:29], v[20:21], v[28:29]
	v_add_u32_e32 v158, 0xdc000, v167
	v_cvt_pk_bf16_f32 v18, v30, v31
	v_cvt_pk_bf16_f32 v19, v32, v33
	v_cvt_pk_bf16_f32 v20, v26, v27
	v_cvt_pk_bf16_f32 v21, v28, v29
	global_store_dwordx4 v158, v[18:21], s[84:85]
	s_waitcnt lgkmcnt(0)
	v_add_f32_e32 v168, v176, v177
	v_add_f32_e32 v169, v178, v179
	v_add_f32_e32 v168, v168, v169
	v_fmamk_f32 v168, v168, 0x3a800000, v225
	v_rsq_f32_e32 v168, v168
	s_nop 0
	v_pk_fma_f32 v[14:15], v[14:15], v[168:169], v[78:79] op_sel_hi:[1,0,1]
	v_pk_fma_f32 v[16:17], v[16:17], v[168:169], v[80:81] op_sel_hi:[1,0,1]
	v_pk_fma_f32 v[10:11], v[10:11], v[168:169], v[70:71] op_sel_hi:[1,0,1]
	v_pk_fma_f32 v[12:13], v[12:13], v[168:169], v[72:73] op_sel_hi:[1,0,1]
	v_pk_fma_f32 v[6:7], v[6:7], v[168:169], v[66:67] op_sel_hi:[1,0,1]
	v_pk_fma_f32 v[8:9], v[8:9], v[168:169], v[68:69] op_sel_hi:[1,0,1]
	v_pk_fma_f32 v[2:3], v[2:3], v[168:169], v[62:63] op_sel_hi:[1,0,1]
	v_pk_fma_f32 v[4:5], v[4:5], v[168:169], v[64:65] op_sel_hi:[1,0,1]
	v_pk_mul_f32 v[170:171], v[14:15], s[2:3] op_sel_hi:[1,0]
	v_pk_mul_f32 v[172:173], v[16:17], s[2:3] op_sel_hi:[1,0]
	v_pk_mul_f32 v[174:175], v[10:11], s[2:3] op_sel_hi:[1,0]
	v_pk_mul_f32 v[180:181], v[12:13], s[2:3] op_sel_hi:[1,0]
	v_exp_f32_e32 v170, v170
	v_exp_f32_e32 v171, v171
	v_exp_f32_e32 v172, v172
	v_exp_f32_e32 v173, v173
	v_exp_f32_e32 v174, v174
	v_exp_f32_e32 v175, v175
	v_exp_f32_e32 v180, v180
	v_exp_f32_e32 v181, v181
	v_pk_add_f32 v[170:171], v[170:171], s[2:3] op_sel:[0,1] op_sel_hi:[1,1]
	v_pk_add_f32 v[172:173], v[172:173], s[2:3] op_sel:[0,1] op_sel_hi:[1,1]
	v_pk_add_f32 v[174:175], v[174:175], s[2:3] op_sel:[0,1] op_sel_hi:[1,1]
	v_pk_add_f32 v[180:181], v[180:181], s[2:3] op_sel:[0,1] op_sel_hi:[1,1]
	v_rcp_f32_e32 v170, v170
	v_rcp_f32_e32 v171, v171
	v_rcp_f32_e32 v172, v172
	v_rcp_f32_e32 v173, v173
	v_rcp_f32_e32 v174, v174
	v_rcp_f32_e32 v175, v175
	v_rcp_f32_e32 v180, v180
	v_rcp_f32_e32 v181, v181
	v_pk_mul_f32 v[14:15], v[14:15], v[170:171]
	v_pk_mul_f32 v[16:17], v[16:17], v[172:173]
	v_pk_mul_f32 v[10:11], v[10:11], v[174:175]
	v_pk_mul_f32 v[12:13], v[12:13], v[180:181]
	v_pk_mul_f32 v[14:15], v[6:7], v[14:15]
	v_pk_mul_f32 v[16:17], v[8:9], v[16:17]
	v_pk_mul_f32 v[10:11], v[2:3], v[10:11]
	v_pk_mul_f32 v[12:13], v[4:5], v[12:13]
	v_add_u32_e32 v158, 0xf2000, v167
	v_cvt_pk_bf16_f32 v2, v14, v15
	v_cvt_pk_bf16_f32 v3, v16, v17
	v_cvt_pk_bf16_f32 v4, v10, v11
	v_cvt_pk_bf16_f32 v5, v12, v13
	global_store_dwordx4 v158, v[2:5], s[84:85]
	s_andn2_b64 vcc, exec, s[0:1]
	s_mov_b64 s[2:3], -1
	s_cbranch_vccnz .LBB0_58
	s_andn2_b64 vcc, exec, s[70:71]
	s_cbranch_vccnz .LBB0_57
	s_barrier
	s_branch .LBB0_57
